# P7 task order rotated over three workgroup groups ((blockIdx>>3)%3): prompt-samples-conv / conv-prompt-samples / samples-conv-prompt, on top of k3
# baseline (speedup 1.0000x reference)
; #define GAS __attribute__((address_space(1)))
; #define LAS __attribute__((address_space(3)))
; __device__ __forceinline__ void prompt_unit(Frame& F, const Args& A, int b, int hk) {
;     const bf16* PROJ = (const bf16*)(A.ws + WS_PROJ); bf16* MIX = (bf16*)(A.ws + WS_MIX);
;     LAS unsigned char* lds = F.lds;
;     fill_lut(lds, A.in[I_RB], hk, F.tid);
;     v4u kqa[8], vqa[8];
; #pragma unroll
;     for (int i = 0; i < 8; ++i) { const int cid = F.tid + 512 * i, kidx = cid >> 4, ch = cid & 15; const int row = 128 * (b - 1) + kidx, rowc = row < 0 ? 0 : row;
;         const bf16* p = PROJ + (size_t)rowc * NPROJ + 128 * hk + 8 * ch; kqa[i] = *(const GAS v4u*)(p + C_K); vqa[i] = *(const GAS v4u*)(p + C_V); }
; #pragma unroll
;     for (int i = 0; i < 8; ++i) { const int cid = F.tid + 512 * i, kidx = cid >> 4, ch = cid & 15; const int row = 128 * (b - 1) + kidx;
;         v4u kq = kqa[i], vq = vqa[i];
;         if (row < 0) { kq = (v4u){0u, 0u, 0u, 0u}; vq = (v4u){0u, 0u, 0u, 0u}; }
;         stage_kv(lds, kidx, ch, kq, vq);
;         if (b == SEQ / 128 - 1 && kidx >= 128) {
;             store8_f32(A.out + O_KWP + (size_t)(kidx - 128) * 512 + 128 * hk + 8 * ch, kq);
;             store8_f32(A.out + O_VWP + (size_t)(kidx - 128) * 512 + 128 * hk + 8 * ch, vq); }
;     }
;     __syncthreads();
;     const int g = F.wave >> 1, half = F.wave & 1, c = F.lane & 31, h = F.lane >> 5, head = 4 * hk + g;
; __device__ __forceinline__ void mixer_phase(Frame& F, const Args& A) {
;     ...
;     for (int u = F.vcu; u < 256 * (PROBE_P7 == 1 ? 2 : 1); u += F.G) prompt_unit(F, A, (u & 255) >> 2, u & 3);
;     for (int u = F.vcu; u < 512 * (PROBE_P7 == 2 ? 2 : 1); u += F.G) sample_unit(F, A, (u & 511) >> 2, u & 3);
;     for (int u = F.vcu * NWAVES + F.wave; u < (M / 8) * 8 * (PROBE_P7 == 3 ? 2 : 1); u += F.G * NWAVES) conv_item(F, A, u % ((M / 8) * 8));
.Lp7_again:
	s_cmpk_eq_i32 s33, 0x100
	s_cbranch_scc0 .Lp7_norm
	s_cmp_eq_u32 s101, 7
	s_cbranch_scc1 .Lp7_norm
	s_cmp_eq_u32 s101, 9
	s_cbranch_scc1 .Lp7_norm
	s_lshr_b32 s0, s50, 3
	s_mul_i32 s1, s0, 43
	s_lshr_b32 s1, s1, 7
	s_mul_i32 s1, s1, 3
	s_sub_i32 s0, s0, s1
	s_cmp_eq_u32 s0, 0
	s_cbranch_scc1 .Lp7_norm
	v_writelane_b32 v253, s17, 0
	v_writelane_b32 v253, s18, 1
	v_writelane_b32 v253, s19, 2
	v_writelane_b32 v253, s20, 3
	v_writelane_b32 v253, s21, 4
	v_writelane_b32 v253, s22, 5
	v_writelane_b32 v253, s23, 6
	v_writelane_b32 v253, s46, 7
	v_writelane_b32 v253, s48, 8
	v_writelane_b32 v253, s54, 9
	v_writelane_b32 v253, s58, 10
	v_writelane_b32 v253, s59, 11
	v_writelane_b32 v253, s60, 12
	v_writelane_b32 v253, s61, 13
	v_writelane_b32 v253, s62, 14
	v_writelane_b32 v253, s63, 15
	v_writelane_b32 v253, s66, 16
	v_writelane_b32 v253, s67, 17
	v_writelane_b32 v253, s71, 18
	v_writelane_b32 v253, s88, 19
	v_writelane_b32 v253, s94, 20
	v_writelane_b32 v253, s95, 21
	v_writelane_b32 v253, s96, 22
	v_writelane_b32 v253, s97, 23
	s_cmp_eq_u32 s0, 2
	s_cbranch_scc1 .Lp7_grpC
	s_mov_b32 s101, 6
	s_mov_b64 s[36:37], s[96:97]
	s_mov_b64 s[38:39], s[58:59]
	s_mov_b64 s[44:45], s[94:95]
	s_branch .LBB0_641
.Lp7_grpC:
	s_mov_b32 s101, 8
.Lp7_norm:
	s_add_i32 s0, 0, 0x11000
	v_readlane_b32 s1, v252, 2
	s_cmpk_gt_i32 s1, 0xff
	s_movk_i32 s1, 0x204
	v_cmp_gt_u32_e64 s[2:3], s1, v0
	v_lshrrev_b32_e32 v163, 4, v0
	v_and_b32_e32 v4, 15, v0
	v_lshrrev_b32_e32 v3, 3, v0
	s_movk_i32 s1, 0x53
	v_mul_u32_u24_e32 v2, 0x1080, v4
	v_and_b32_e32 v154, 8, v3
	v_and_b32_e32 v3, 8, v163
	v_bitop3_b32 v151, v163, s1, 64 bitop3:0xc8
	s_movk_i32 s1, 0x93
	v_mov_b32_e32 v156, 0x80
	v_add3_u32 v155, s0, v2, v3
	v_bitop3_b32 v2, v163, s1, v156 bitop3:0xc8
	v_lshlrev_b32_e32 v3, 1, v2
	v_lshlrev_b32_e32 v2, 1, v154
	v_add3_u32 v170, v155, v3, v2
	v_and_b32_e32 v150, 31, v0
	v_lshrrev_b32_e32 v3, 2, v0
	v_lshrrev_b32_e32 v6, 5, v162
	v_and_b32_e32 v5, 8, v3
	v_lshlrev_b32_e32 v7, 4, v6
	v_lshlrev_b32_e32 v149, 2, v6
	v_mul_u32_u24_e32 v6, 0x210, v150
	v_lshlrev_b32_e32 v171, 3, v4
	s_mov_b32 s9, 0
	s_movk_i32 s14, 0x110
	v_mul_u32_u24_e32 v165, 0x110, v163
	v_lshlrev_b32_e32 v153, 4, v4
	v_and_b32_e32 v152, 19, v163
	v_mov_b32_e32 v111, 0
	v_add_u32_e32 v148, 0, v7
	v_add3_u32 v172, s0, v7, v6
	v_lshlrev_b32_e32 v122, 1, v5
	v_lshlrev_b32_e32 v124, 1, v149
	v_lshlrev_b32_e32 v126, 2, v171
	s_cbranch_scc1 .LBB0_627
	s_cmp_eq_u32 s101, 8
	s_cbranch_scc1 .LBB0_627
	v_or_b32_e32 v4, 0x200, v0
	v_lshrrev_b32_e32 v159, 4, v4
	v_lshrrev_b32_e32 v4, 3, v4
	v_and_b32_e32 v4, 0x66, v4
	v_and_b32_e32 v3, 16, v3
	v_or_b32_e32 v5, 0x600, v0
	v_add3_u32 v173, v155, v4, v3
	v_lshlrev_b32_e32 v4, 1, v151
	v_add3_u32 v174, v155, v4, v2
	v_lshrrev_b32_e32 v4, 3, v5
	v_or_b32_e32 v6, 0xa00, v0
	v_and_b32_e32 v4, 0xe6, v4
	v_add3_u32 v175, v155, v4, v3
	v_lshrrev_b32_e32 v4, 3, v6
	s_movk_i32 s0, 0x1ff
	v_and_b32_e32 v4, 0x166, v4
	v_cmp_lt_u32_e64 s[4:5], s0, v0
	v_add3_u32 v176, v155, v4, v3
	s_movk_i32 s0, 0xd3
	v_mov_b32_e32 v4, 0xc0
	s_lshr_b32 s15, s71, 7
	v_bitop3_b32 v4, v163, s0, v4 bitop3:0xc8
	s_mul_i32 s0, s15, 0x210
	s_bfe_u32 s8, s71, 0x10006
	s_add_i32 s17, s0, 0
	s_lshl_b32 s16, s8, 1
	s_add_i32 s17, s17, 0x21800
	v_or_b32_e32 v7, 0xe00, v0
	v_lshlrev_b32_e32 v8, 1, v152
	v_lshlrev_b32_e32 v4, 1, v4
	s_add_u32 s0, s28, 0x9000000
	v_and_b32_e32 v110, 0xf0, v164
	v_lshrrev_b32_e32 v160, 4, v5
	v_add3_u32 v169, v155, v8, v2
	v_add3_u32 v177, v155, v4, v2
	v_lshrrev_b32_e32 v2, 3, v7
	s_addc_u32 s1, s29, 0
	v_lshl_add_u64 v[112:113], s[52:53], 0, v[110:111]
	v_and_b32_e32 v2, 0x1e6, v2
	v_or_b32_e32 v110, 0xffffff80, v160
	s_add_u32 s6, s28, 0x9040000
	v_add3_u32 v178, v155, v2, v3
	v_lshlrev_b64 v[2:3], 11, v[110:111]
	s_addc_u32 s7, s29, 0
	v_lshl_add_u64 v[4:5], s[0:1], 0, v[2:3]
	v_mov_b32_e32 v127, v111
	v_lshl_add_u64 v[2:3], s[6:7], 0, v[2:3]
	v_lshlrev_b32_e32 v110, 11, v163
	v_lshl_add_u64 v[120:121], v[2:3], 0, v[126:127]
	v_lshl_add_u64 v[2:3], s[0:1], 0, v[110:111]
	v_lshrrev_b32_e32 v161, 4, v6
	v_lshl_add_u64 v[128:129], v[2:3], 0, v[126:127]
	v_lshl_add_u64 v[2:3], s[6:7], 0, v[110:111]
	v_lshl_add_u64 v[130:131], v[2:3], 0, v[126:127]
	v_lshlrev_b32_e32 v2, 11, v161
	v_mov_b32_e32 v3, v111
	v_lshl_add_u64 v[118:119], v[4:5], 0, v[126:127]
	v_add_u32_e32 v4, 0xfffc0000, v2
	v_lshl_add_u64 v[2:3], s[0:1], 0, v[2:3]
	v_or_b32_e32 v110, 0x20000, v110
	v_lshl_add_u64 v[134:135], v[2:3], 0, v[126:127]
	v_lshl_add_u64 v[2:3], s[0:1], 0, v[110:111]
	v_lshl_add_u64 v[136:137], v[2:3], 0, v[126:127]
	v_lshl_add_u64 v[2:3], s[6:7], 0, v[110:111]
	v_lshrrev_b32_e32 v167, 4, v7
	v_lshl_add_u64 v[138:139], v[2:3], 0, v[126:127]
	v_mov_b32_e32 v2, 0xfffc0000
	v_lshl_add_u32 v110, v167, 11, v2
	v_lshl_add_u64 v[2:3], s[0:1], 0, v[110:111]
	v_lshl_add_u64 v[140:141], v[2:3], 0, v[126:127]
	v_lshl_add_u64 v[2:3], s[6:7], 0, v[110:111]
	v_mov_b32_e32 v5, v111
	v_lshl_add_u64 v[142:143], v[2:3], 0, v[126:127]
	v_mbcnt_lo_u32_b32 v2, -1, 0
	v_lshl_add_u64 v[4:5], s[0:1], 0, v[4:5]
	v_mbcnt_hi_u32_b32 v2, -1, v2
	v_lshl_add_u64 v[132:133], v[4:5], 0, v[126:127]
	v_and_b32_e32 v4, 64, v2
	v_xor_b32_e32 v3, 32, v2
	v_add_u32_e32 v4, 64, v4
	v_add_u32_e32 v168, 0, v165
	v_cmp_lt_i32_e32 vcc, v3, v4
	v_mad_u32_u24 v8, v159, s14, 0
	v_mad_u32_u24 v9, v160, s14, 0
	v_add_u32_e32 v10, 0x8800, v168
	v_mad_u32_u24 v11, v161, s14, 0
	v_mad_u32_u24 v6, v167, s14, 0
	v_mov_b32_e32 v123, v111
	v_mov_b32_e32 v125, v111
	v_cndmask_b32_e32 v2, v2, v3, vcc
	v_or_b32_e32 v157, 64, v163
	v_or_b32_e32 v158, 0x80, v163
	v_or_b32_e32 v166, 0xc0, v163
	v_lshl_add_u64 v[114:115], s[52:53], 0, v[122:123]
	v_lshl_add_u64 v[116:117], s[42:43], 0, v[124:125]
	v_lshlrev_b32_e32 v123, 2, v2
	v_lshl_or_b32 v125, s8, 6, v150
	s_movk_i32 s18, 0x3f81
	s_movk_i32 s19, 0x81
	s_movk_i32 s20, 0x42
	s_movk_i32 s21, 0x4c
	s_movk_i32 s22, 0x56
	s_movk_i32 s23, 0x62
	s_movk_i32 s48, 0x70
	s_movk_i32 s49, 0x4800
	v_add_u32_e32 v127, v8, v153
	v_add_u32_e32 v179, v9, v153
	v_add_u32_e32 v180, v11, v153
	v_add_u32_e32 v181, v6, v153
	s_movk_i32 s54, 0x7fff
	v_add_u32_e32 v182, v10, v153
	v_mov_b32_e32 v183, 0xf149f2ca
	v_mov_b32_e32 v184, 1
	v_readlane_b32 s55, v252, 2

; __device__ __forceinline__ void sample_unit(Frame& F, const Args& A, int s, int hk) {
;     const bf16* PROJ = (const bf16*)(A.ws + WS_PROJ); bf16* MIX = (bf16*)(A.ws + WS_MIX);
;     LAS unsigned char* lds = F.lds;
;     fill_lut(lds, A.in[I_RB], hk, F.tid);
;     {
;         const int ch = F.tid & 15, kb0 = F.tid >> 4;
;         f32x4 ck[4][2], cv[4][2];
; #pragma unroll
;         for (int i = 0; i < 4; ++i) { const size_t off = (((size_t)s * 128 + kb0 + 32 * i) * 4 + hk) * 128 + 8 * ch;
;             ck[i][0] = *(const GAS f32x4*)(A.in[I_CK] + off); ck[i][1] = *(const GAS f32x4*)(A.in[I_CK] + off + 4);
;             cv[i][0] = *(const GAS f32x4*)(A.in[I_CV] + off); cv[i][1] = *(const GAS f32x4*)(A.in[I_CV] + off + 4); }
;         const int kn = 128 + kb0, knc = kn < 136 ? kn : 135;
;         const bf16* pn = PROJ + (size_t)(SEQ + 8 * s + (knc - 128)) * NPROJ + 128 * hk + 8 * ch;
;         v4u nkq = *(const GAS v4u*)(pn + C_K), nvq = *(const GAS v4u*)(pn + C_V);
; #pragma unroll
;         for (int i = 0; i < 4; ++i) { const int kidx = kb0 + 32 * i; const f32x4 k0 = ck[i][0], k1 = ck[i][1], v0 = cv[i][0], v1 = cv[i][1];
;             const v4u kq = (v4u){pg8::cvt_pk_bf16(k0[0], k0[1]), pg8::cvt_pk_bf16(k0[2], k0[3]), pg8::cvt_pk_bf16(k1[0], k1[1]), pg8::cvt_pk_bf16(k1[2], k1[3])};
;             const v4u vq = (v4u){pg8::cvt_pk_bf16(v0[0], v0[1]), pg8::cvt_pk_bf16(v0[2], v0[3]), pg8::cvt_pk_bf16(v1[0], v1[1]), pg8::cvt_pk_bf16(v1[2], v1[3])};
;             if (kidx >= 8) {
;                 float* ko = A.out + O_KWS + (((size_t)s * 128 + (kidx - 8)) * 4 + hk) * 128 + 8 * ch; *(GAS f32x4*)ko = k0; *(GAS f32x4*)(ko + 4) = k1;
;                 float* vo = A.out + O_VWS + (((size_t)s * 128 + (kidx - 8)) * 4 + hk) * 128 + 8 * ch; *(GAS f32x4*)vo = v0; *(GAS f32x4*)(vo + 4) = v1; }
;             stage_kv(lds, kidx, ch, kq, vq); }
;         if (kn < 136) {
;             store8_f32(A.out + O_KWS + (((size_t)s * 128 + (kn - 8)) * 4 + hk) * 128 + 8 * ch, nkq);
;             store8_f32(A.out + O_VWS + (((size_t)s * 128 + (kn - 8)) * 4 + hk) * 128 + 8 * ch, nvq);
;         } else { nkq = (v4u){0u, 0u, 0u, 0u}; nvq = (v4u){0u, 0u, 0u, 0u}; }
;         stage_kv(lds, kn, ch, nkq, nvq);
;     }
;     __syncthreads();
;     if (F.wave == 0) {
;         const int c = F.lane & 31, h = F.lane >> 5, g = c >> 3, t = c & 7, head = 4 * hk + g, row = SEQ + 8 * s + t;
.LBB0_627:
	v_readlane_b32 s0, v252, 2
	s_mov_b64 s[44:45], s[94:95]
	s_mov_b64 s[38:39], s[58:59]
	s_mov_b64 s[36:37], s[96:97]
	s_cmp_eq_u32 s101, 9
	s_cbranch_scc0 .Lp7_h2
	s_mov_b32 s101, 0
	s_branch .LBB0_659
.Lp7_h2:
	s_cmpk_gt_i32 s0, 0x1ff
	s_cbranch_scc1 .LBB0_641
	s_movk_i32 s0, 0x80
	v_cmp_gt_u32_e64 s[4:5], s0, v0
	s_movk_i32 s0, 0x7f
	v_mov_b32_e32 v127, 0
	v_cmp_lt_u32_e64 s[6:7], s0, v0
	v_lshl_add_u64 v[2:3], s[28:29], 0, v[126:127]
	s_mov_b64 s[0:1], 0x9084000
	v_lshl_add_u64 v[128:129], v[2:3], 0, s[0:1]
	s_mov_b64 s[0:1], 0xb084000
	v_lshl_add_u32 v4, v154, 1, v155
	v_lshl_add_u64 v[130:131], v[2:3], 0, s[0:1]
	v_bitop3_b32 v3, v163, 51, 32 bitop3:0xc8
	v_lshl_add_u32 v178, v3, 1, v4
	s_movk_i32 s1, 0x73
	v_mov_b32_e32 v3, 0x60
	s_cmp_lt_u32 s71, 64
	v_and_b32_e32 v184, 7, v0
	v_bitop3_b32 v3, v163, s1, v3 bitop3:0xc8
	s_cselect_b64 s[54:55], -1, 0
	s_add_i32 s0, 0, 0x21800
	v_or_b32_e32 v5, 0x80, v184
	v_lshl_add_u32 v176, v152, 1, v4
	v_lshl_add_u32 v180, v151, 1, v4
	v_lshl_add_u32 v182, v3, 1, v4
	v_bfe_u32 v183, v0, 3, 2
	s_movk_i32 s8, 0x210
	v_mov_b32_e32 v4, s0
	v_sub_u32_e32 v6, v5, v149
	v_mad_u32_u24 v4, v183, s8, v4
	v_sub_u32_e64 v8, v6, 41 clamp
	v_lshl_add_u32 v196, v8, 2, v4
	v_sub_u32_e64 v8, v6, 43 clamp
	v_min_u32_e32 v7, 0x80, v6
	v_lshl_add_u32 v197, v8, 2, v4
	v_sub_u32_e64 v8, v6, 49 clamp
	s_movk_i32 s22, 0x81
	v_lshl_add_u32 v185, v7, 2, v4
	v_xad_u32 v7, v149, -1, v5
	v_lshl_add_u32 v198, v8, 2, v4
	v_sub_u32_e64 v8, v6, 51 clamp
	v_cmp_gt_u32_e64 s[90:91], s22, v7
	v_min_u32_e32 v7, 0x80, v7
	v_lshl_add_u32 v199, v8, 2, v4
	v_sub_u32_e64 v8, v6, 57 clamp
	v_lshl_add_u32 v186, v7, 2, v4
	v_or_b32_e32 v7, 2, v149
	v_lshl_add_u32 v200, v8, 2, v4
	v_sub_u32_e64 v8, v6, 59 clamp
	s_movk_i32 s16, 0x49
	v_sub_u32_e32 v7, v5, v7
	v_lshl_add_u32 v201, v8, 2, v4
	v_sub_u32_e64 v8, v6, s16 clamp
	s_movk_i32 s16, 0x4b
	v_cmp_gt_u32_e64 s[92:93], s22, v7
	v_min_u32_e32 v7, 0x80, v7
	v_lshl_add_u32 v202, v8, 2, v4
	v_sub_u32_e64 v8, v6, s16 clamp
	s_movk_i32 s16, 0x51
	v_lshl_add_u32 v187, v7, 2, v4
	v_or_b32_e32 v7, 3, v149
	v_lshl_add_u32 v203, v8, 2, v4
	v_sub_u32_e64 v8, v6, s16 clamp
	s_movk_i32 s16, 0x53
	v_sub_u32_e32 v7, v5, v7
	v_lshl_add_u32 v204, v8, 2, v4
	v_sub_u32_e64 v8, v6, s16 clamp
	s_movk_i32 s16, 0x59
	v_cmp_gt_u32_e64 s[94:95], s22, v7
	v_min_u32_e32 v7, 0x80, v7
	v_lshl_add_u32 v205, v8, 2, v4
	v_sub_u32_e64 v8, v6, s16 clamp
	s_movk_i32 s16, 0x5b
	v_lshl_add_u32 v188, v7, 2, v4
	v_sub_u32_e64 v7, v6, 9 clamp
	v_lshl_add_u32 v206, v8, 2, v4
	v_sub_u32_e64 v8, v6, s16 clamp
	s_movk_i32 s16, 0x69
	v_lshl_add_u32 v189, v7, 2, v4
	v_sub_u32_e64 v7, v6, 11 clamp
	v_lshl_add_u32 v207, v8, 2, v4
	v_sub_u32_e64 v8, v6, s16 clamp
	s_movk_i32 s16, 0x6b
	v_lshl_add_u32 v190, v7, 2, v4
	v_sub_u32_e64 v7, v6, 17 clamp
	v_lshl_add_u32 v208, v8, 2, v4
	v_sub_u32_e64 v8, v6, s16 clamp
	s_movk_i32 s16, 0x71
	v_lshl_add_u32 v191, v7, 2, v4
	v_sub_u32_e64 v7, v6, 19 clamp
	v_lshl_add_u32 v209, v8, 2, v4
	v_sub_u32_e64 v8, v6, s16 clamp
	v_lshl_add_u32 v192, v7, 2, v4
	v_sub_u32_e64 v7, v6, 25 clamp
	v_lshl_add_u32 v210, v8, 2, v4
	v_sub_u32_e64 v8, v6, s1 clamp
	s_movk_i32 s1, 0x79
	v_lshl_add_u32 v193, v7, 2, v4
	v_sub_u32_e64 v7, v6, 27 clamp
	v_lshl_add_u32 v211, v8, 2, v4
	v_sub_u32_e64 v8, v6, s1 clamp
	s_movk_i32 s1, 0x7b
	v_cmp_gt_u32_e64 s[88:89], s22, v6
	v_lshl_add_u32 v194, v7, 2, v4
	v_sub_u32_e32 v7, v184, v149
	v_sub_u32_e64 v6, v6, s1 clamp
	v_lshl_add_u32 v213, v6, 2, v4
	v_max_i32_e32 v6, 0, v7
	v_lshl_add_u32 v214, v6, 2, v4
	v_or_b32_e32 v6, 0x81, v149
	v_sub_u32_e32 v6, v5, v6
	v_cmp_gt_u32_e64 s[70:71], s22, v6
	v_max_i32_e32 v6, 0, v6
	v_lshl_add_u32 v215, v6, 2, v4
	v_or_b32_e32 v6, 0x82, v149
	v_sub_u32_e32 v6, v5, v6
	v_cmp_gt_u32_e64 s[58:59], s22, v6
	v_max_i32_e32 v6, 0, v6
	v_or_b32_e32 v2, 32, v163
	v_lshl_add_u32 v216, v6, 2, v4
	v_or_b32_e32 v6, 0x83, v149
	v_add_u32_e32 v175, 0, v153
	v_mul_u32_u24_e32 v2, 0x110, v2
	v_sub_u32_e32 v5, v5, v6
	v_mul_u32_u24_e32 v3, 0x110, v150
	v_cmp_gt_u32_e64 s[96:97], s22, v5
	v_max_i32_e32 v5, 0, v5
	v_add_u32_e32 v218, v175, v2
	v_mbcnt_lo_u32_b32 v2, -1, 0
	v_add_u32_e32 v173, -8, v163
	v_cndmask_b32_e64 v174, 7, v163, s[4:5]
	s_mov_b32 s49, 0
	v_add_u32_e32 v177, 24, v163
	v_add_u32_e32 v179, 56, v163
	v_add_u32_e32 v181, 0x58, v163
	v_lshl_add_u32 v195, v7, 2, v4
	v_lshl_add_u32 v212, v8, 2, v4
	v_cmp_gt_u32_e64 s[46:47], s22, v7
	v_lshl_add_u32 v217, v5, 2, v4
	s_movk_i32 s1, 0x42
	s_movk_i32 s26, 0x4c
	s_movk_i32 s27, 0x56
	s_movk_i32 s34, 0x62
	s_movk_i32 s78, 0x70
	s_movk_i32 s79, 0x1000
	v_add_u32_e32 v219, v148, v3
	s_mov_b32 s84, 0xf149f2ca
	s_movk_i32 s85, 0x7fff
	v_mov_b32_e32 v220, 0x3c000
	v_mov_b32_e32 v221, 0xf149f2ca
	v_mbcnt_hi_u32_b32 v222, -1, v2
	v_mov_b32_e32 v223, 1
	v_readlane_b32 s86, v252, 2
	s_branch .LBB0_630

; __device__ __forceinline__ void mixer_phase(Frame& F, const Args& A) {
;     ...
;     for (int u = F.vcu; u < 256 * (PROBE_P7 == 1 ? 2 : 1); u += F.G) prompt_unit(F, A, (u & 255) >> 2, u & 3);
;     for (int u = F.vcu; u < 512 * (PROBE_P7 == 2 ? 2 : 1); u += F.G) sample_unit(F, A, (u & 511) >> 2, u & 3);
;     for (int u = F.vcu * NWAVES + F.wave; u < (M / 8) * 8 * (PROBE_P7 == 3 ? 2 : 1); u += F.G * NWAVES) conv_item(F, A, u % ((M / 8) * 8));
.LBB0_658:
	s_mov_b64 s[94:95], s[44:45]
	s_cmp_eq_u32 s101, 6
	s_cbranch_scc1 .Lp7_retB
	s_cmp_eq_u32 s101, 8
	s_cbranch_scc0 .LBB0_659
	s_mov_b32 s101, 9
	s_branch .Lp7_ret
.Lp7_retB:
	s_mov_b32 s101, 7
.Lp7_ret:
	v_readlane_b32 s17, v253, 0
	v_readlane_b32 s18, v253, 1
	v_readlane_b32 s19, v253, 2
	v_readlane_b32 s20, v253, 3
	v_readlane_b32 s21, v253, 4
	v_readlane_b32 s22, v253, 5
	v_readlane_b32 s23, v253, 6
	v_readlane_b32 s46, v253, 7
	v_readlane_b32 s48, v253, 8
	v_readlane_b32 s54, v253, 9
	v_readlane_b32 s58, v253, 10
	v_readlane_b32 s59, v253, 11
	v_readlane_b32 s60, v253, 12
	v_readlane_b32 s61, v253, 13
	v_readlane_b32 s62, v253, 14
	v_readlane_b32 s63, v253, 15
	v_readlane_b32 s66, v253, 16
	v_readlane_b32 s67, v253, 17
	v_readlane_b32 s71, v253, 18
	v_readlane_b32 s88, v253, 19
	v_readlane_b32 s94, v253, 20
	v_readlane_b32 s95, v253, 21
	v_readlane_b32 s96, v253, 22
	v_readlane_b32 s97, v253, 23
	s_nop 7
	s_branch .Lp7_again
